# attention no-mask step bodies: packed fp32 v_pk_mul/v_pk_add replaced by the scalar ops they stand for (bit-identical), per asm guide 7.5
# speedup vs baseline: 1.0109x; 1.0109x over previous
.Lattn_fast_B:
	s_waitcnt lgkmcnt(1)
	v_mfma_f32_32x32x16_bf16 v[66:81], v[138:141], v[94:97], v[66:81]
	s_waitcnt lgkmcnt(0)
	v_mfma_f32_32x32x16_bf16 v[50:65], v[142:145], v[94:97], v[50:65]
	ds_read_b128 v[138:141], v134 offset:37120
	ds_read_b128 v[142:145], v134 offset:37136
	s_waitcnt lgkmcnt(1)
	s_nop 6
	v_add_f32_e32 v138, v66, v138
	v_add_f32_e32 v137, v67, v139
	s_mov_b32 s0, 0xf149f2ca
	v_add_f32_e32 v139, v68, v140
	v_max3_f32 v66, v138, s0, v137
	v_add_f32_e32 v140, v69, v141
	s_waitcnt lgkmcnt(0)
	v_add_f32_e32 v141, v70, v142
	v_add_f32_e32 v142, v71, v143
	v_add_f32_e32 v143, v72, v144
	v_max3_f32 v66, v66, v139, v140
	v_add_f32_e32 v144, v73, v145
	v_max3_f32 v66, v66, v141, v142
	v_max3_f32 v145, v66, v143, v144
	ds_read_b128 v[66:69], v134 offset:37184
	ds_read_b128 v[70:73], v134 offset:37200
	s_waitcnt lgkmcnt(1)
	v_add_f32_e32 v74, v74, v66
	v_add_f32_e32 v75, v75, v67
	v_add_f32_e32 v76, v76, v68
	v_add_f32_e32 v77, v77, v69
	s_waitcnt lgkmcnt(0)
	v_add_f32_e32 v78, v78, v70
	v_add_f32_e32 v67, v79, v71
	v_max3_f32 v66, v145, v74, v75
	v_mov_b32_e32 v145, v67
	v_add_f32_e32 v148, v80, v72
	v_max3_f32 v66, v66, v76, v77
	v_add_f32_e32 v81, v81, v73
	v_max3_f32 v66, v66, v78, v145
	v_max3_f32 v79, v66, v148, v81
	ds_read_b128 v[66:69], v134 offset:37248
	ds_read_b128 v[70:73], v134 offset:37264
	s_waitcnt lgkmcnt(1)
	v_add_f32_e32 v66, v50, v66
	v_add_f32_e32 v67, v51, v67
	v_add_f32_e32 v68, v52, v68
	v_add_f32_e32 v69, v53, v69
	s_waitcnt lgkmcnt(0)
	v_add_f32_e32 v70, v54, v70
	v_add_f32_e32 v71, v55, v71
	v_add_f32_e32 v72, v56, v72
	v_max3_f32 v50, v79, v66, v67
	v_max3_f32 v50, v50, v68, v69
	v_add_f32_e32 v73, v57, v73
	v_max3_f32 v50, v50, v70, v71
	v_max3_f32 v79, v50, v72, v73
	ds_read_b128 v[50:53], v134 offset:37312
	ds_read_b128 v[54:57], v134 offset:37328
	s_waitcnt lgkmcnt(1)
	v_add_f32_e32 v149, v58, v50
	v_add_f32_e32 v80, v59, v51
	v_add_f32_e32 v51, v60, v52
	v_max3_f32 v50, v79, v149, v80
	v_mov_b32_e32 v79, v51
	v_add_f32_e32 v53, v61, v53
	s_waitcnt lgkmcnt(0)
	v_add_f32_e32 v62, v62, v54
	v_add_f32_e32 v162, v63, v55
	v_add_f32_e32 v163, v64, v56
	v_add_u32_e32 v0, 0x77, v0
	v_max3_f32 v50, v50, v79, v53
	v_add_f32_e32 v57, v65, v57
	v_max3_f32 v50, v50, v62, v162
	v_and_b32_e32 v51, 64, v207
	v_max3_f32 v0, v50, v163, v57
	v_xor_b32_e32 v50, 32, v207
	v_add_u32_e32 v51, 64, v51
	v_cmp_lt_i32_e32 vcc, v50, v51
	s_nop 1
	v_cndmask_b32_e32 v50, v207, v50, vcc
	v_lshlrev_b32_e32 v50, 2, v50
	ds_bpermute_b32 v50, v50, v0
	s_waitcnt lgkmcnt(0)
	v_max3_f32 v63, v136, v0, v50
	v_sub_f32_e32 v0, v138, v63
	v_exp_f32_e32 v164, v0
	v_sub_f32_e32 v0, v66, v63
	v_sub_f32_e32 v52, v139, v63
	v_exp_f32_e32 v165, v0
	v_sub_f32_e32 v0, v137, v63
	v_exp_f32_e32 v166, v52
	v_sub_f32_e32 v52, v68, v63
	v_sub_f32_e32 v56, v141, v63
	v_sub_f32_e32 v53, v53, v63
	v_exp_f32_e32 v50, v0
	v_sub_f32_e32 v0, v67, v63
	v_exp_f32_e32 v167, v52
	v_sub_f32_e32 v52, v140, v63
	v_exp_f32_e32 v140, v56
	v_sub_f32_e32 v56, v70, v63
	v_sub_f32_e32 v60, v143, v63
	v_sub_f32_e32 v67, v76, v63
	v_exp_f32_e32 v76, v53
	v_sub_f32_e32 v53, v78, v63
	v_exp_f32_e32 v141, v56
	v_sub_f32_e32 v56, v142, v63
	v_exp_f32_e32 v142, v60
	v_sub_f32_e32 v60, v72, v63
	v_sub_f32_e32 v66, v74, v63
	v_exp_f32_e32 v170, v53
	v_sub_f32_e32 v53, v62, v63
	v_exp_f32_e32 v0, v0
	v_exp_f32_e32 v143, v60
	v_sub_f32_e32 v60, v144, v63
	v_exp_f32_e32 v144, v66
	v_sub_f32_e32 v66, v149, v63
	v_exp_f32_e32 v171, v53
	v_sub_f32_e32 v53, v145, v63
	v_exp_f32_e32 v149, v66
	v_sub_f32_e32 v66, v75, v63
	v_exp_f32_e32 v78, v53
	v_sub_f32_e32 v53, v162, v63
	v_exp_f32_e32 v54, v52
	v_sub_f32_e32 v52, v69, v63
	v_exp_f32_e32 v68, v66
	v_sub_f32_e32 v66, v80, v63
	v_exp_f32_e32 v80, v53
	v_sub_f32_e32 v53, v148, v63
	v_add_f32_e32 v51, v164, v165
	v_exp_f32_e32 v52, v52
	v_exp_f32_e32 v145, v53
	v_sub_f32_e32 v53, v163, v63
	v_exp_f32_e32 v58, v56
	v_sub_f32_e32 v56, v71, v63
	v_exp_f32_e32 v148, v53
	v_sub_f32_e32 v53, v81, v63
	v_add_f32_e32 v70, v50, v0
	v_add_f32_e32 v71, v51, v1
	v_sub_f32_e32 v65, v136, v63
	v_exp_f32_e32 v136, v53
	v_sub_f32_e32 v53, v57, v63
	v_add_f32_e32 v71, v70, v71
	v_add_f32_e32 v55, v166, v167
	v_exp_f32_e32 v56, v56
	v_exp_f32_e32 v138, v53
	v_mov_b32_e32 v53, v71
	v_add_f32_e32 v70, v54, v52
	v_add_f32_e32 v71, v55, v53
	v_sub_f32_e32 v64, v73, v63
	v_add_f32_e32 v71, v70, v71
	v_add_f32_e32 v59, v140, v141
	v_exp_f32_e32 v60, v60
	v_exp_f32_e32 v64, v64
	v_mov_b32_e32 v57, v71
	v_add_f32_e32 v70, v58, v56
	v_add_f32_e32 v71, v59, v57
	v_add_f32_e32 v61, v142, v143
	v_add_f32_e32 v71, v70, v71
	v_exp_f32_e32 v66, v66
	v_exp_f32_e32 v62, v65
	v_mov_b32_e32 v65, v71
	v_exp_f32_e32 v168, v67
	v_sub_f32_e32 v67, v79, v63
	v_add_f32_e32 v70, v60, v64
	v_add_f32_e32 v71, v61, v65
	v_exp_f32_e32 v169, v67
	v_sub_f32_e32 v67, v77, v63
	v_add_f32_e32 v71, v70, v71
	v_add_f32_e32 v69, v144, v149
	v_exp_f32_e32 v74, v67
	v_mov_b32_e32 v67, v71
	v_add_f32_e32 v70, v68, v66
	v_add_f32_e32 v71, v69, v67
	v_add_f32_e32 v75, v168, v169
	v_add_f32_e32 v71, v70, v71
	v_mov_b32_e32 v77, v71
	v_add_f32_e32 v70, v74, v76
	v_add_f32_e32 v71, v75, v77
	v_add_f32_e32 v79, v170, v171
	v_add_f32_e32 v71, v70, v71
	v_mov_b32_e32 v81, v71
	v_add_f32_e32 v70, v78, v80
	v_add_f32_e32 v71, v79, v81
	v_add_f32_e32 v137, v145, v148
	v_add_f32_e32 v71, v70, v71
	v_mov_b32_e32 v139, v71
	v_add_f32_e32 v70, v136, v138
	v_add_f32_e32 v71, v137, v139
	v_cvt_pk_bf16_f32 v72, v140, v58
	v_add_f32_e32 v65, v70, v71
	v_cvt_pk_bf16_f32 v71, v166, v54
	v_cvt_pk_bf16_f32 v54, v165, v0
	v_add_u32_e32 v0, v132, v122
	v_cvt_pk_bf16_f32 v70, v164, v50
	v_cvt_pk_bf16_f32 v73, v142, v60
	v_cvt_pk_bf16_f32 v58, v144, v68
	v_cvt_pk_bf16_f32 v59, v168, v74
	v_cvt_pk_bf16_f32 v60, v170, v78
	v_cvt_pk_bf16_f32 v55, v167, v52
	v_cvt_pk_bf16_f32 v50, v149, v66
	v_cvt_pk_bf16_f32 v51, v169, v76
	v_cvt_pk_bf16_f32 v52, v171, v80
	ds_read_b128 v[66:69], v0 offset:32256
	ds_read_b128 v[74:77], v0 offset:27648
	ds_read_b128 v[78:81], v0 offset:27680
	v_mul_f32_e32 v16, v62, v16
	v_mul_f32_e32 v17, v62, v17
	v_mul_f32_e32 v14, v62, v14
	v_mul_f32_e32 v15, v62, v15
	v_mul_f32_e32 v12, v62, v12
	v_mul_f32_e32 v13, v62, v13
	v_mul_f32_e32 v10, v62, v10
	v_mul_f32_e32 v11, v62, v11
	v_mul_f32_e32 v8, v62, v8
	v_mul_f32_e32 v9, v62, v9
	v_mul_f32_e32 v6, v62, v6
	v_mul_f32_e32 v7, v62, v7
	v_mul_f32_e32 v4, v62, v4
	v_mul_f32_e32 v5, v62, v5
	v_mul_f32_e32 v2, v62, v2
	v_mul_f32_e32 v3, v62, v3
	v_mul_f32_e32 v32, v62, v32
	v_mul_f32_e32 v33, v62, v33
	v_mul_f32_e32 v30, v62, v30
	v_mul_f32_e32 v31, v62, v31
	v_mul_f32_e32 v28, v62, v28
	v_mul_f32_e32 v29, v62, v29
	v_mul_f32_e32 v26, v62, v26
	v_mul_f32_e32 v27, v62, v27
	v_mul_f32_e32 v24, v62, v24
	v_mul_f32_e32 v25, v62, v25
	v_mul_f32_e32 v22, v62, v22
	v_mul_f32_e32 v23, v62, v23
	v_mul_f32_e32 v20, v62, v20
	v_mul_f32_e32 v21, v62, v21
	v_mul_f32_e32 v18, v62, v18
	v_mul_f32_e32 v19, v62, v19
	s_waitcnt lgkmcnt(2)
	v_mfma_f32_32x32x16_bf16 v[2:17], v[66:69], v[70:73], v[2:17]
	ds_read_b128 v[66:69], v0 offset:32288
	v_cvt_pk_bf16_f32 v61, v145, v136
	v_cvt_pk_bf16_f32 v56, v141, v56
	v_cvt_pk_bf16_f32 v57, v143, v64
	v_cvt_pk_bf16_f32 v53, v148, v138
	v_fmac_f32_e32 v65, v133, v62
	v_mov_b32_e32 v136, v63
	s_waitcnt lgkmcnt(2)
	v_mfma_f32_32x32x16_bf16 v[18:33], v[74:77], v[70:73], v[18:33]
	v_mov_b32_e32 v133, v65
	s_waitcnt lgkmcnt(1)
	v_mfma_f32_32x32x16_bf16 v[18:33], v[78:81], v[58:61], v[18:33]
	s_waitcnt lgkmcnt(0)
	v_mfma_f32_32x32x16_bf16 v[2:17], v[66:69], v[58:61], v[2:17]
	ds_read_b128 v[58:61], v0 offset:27712
	ds_read_b128 v[66:69], v0 offset:32320
	s_waitcnt lgkmcnt(1)
	v_mfma_f32_32x32x16_bf16 v[18:33], v[58:61], v[54:57], v[18:33]
	s_waitcnt lgkmcnt(0)
	v_mfma_f32_32x32x16_bf16 v[2:17], v[66:69], v[54:57], v[2:17]
	ds_read_b128 v[54:57], v0 offset:27744
	ds_read_b128 v[58:61], v0 offset:32352
	s_waitcnt lgkmcnt(1)
	v_mfma_f32_32x32x16_bf16 v[18:33], v[54:57], v[50:53], v[18:33]
	s_waitcnt lgkmcnt(0)
	v_mfma_f32_32x32x16_bf16 v[2:17], v[58:61], v[50:53], v[2:17]
	s_branch .LBB0_402
.Lattn_fast_A:
	s_waitcnt lgkmcnt(1)
	v_mfma_f32_32x32x16_bf16 v[66:81], v[138:141], v[94:97], v[66:81]
	s_waitcnt lgkmcnt(0)
	v_mfma_f32_32x32x16_bf16 v[50:65], v[142:145], v[94:97], v[50:65]
	ds_read_b128 v[138:141], v134 offset:36864
	ds_read_b128 v[142:145], v134 offset:36880
	s_waitcnt lgkmcnt(1)
	s_nop 6
	v_add_f32_e32 v137, v66, v138
	v_add_f32_e32 v138, v67, v139
	s_mov_b32 s0, 0xf149f2ca
	v_add_f32_e32 v139, v68, v140
	v_max3_f32 v66, v137, s0, v138
	v_add_f32_e32 v140, v69, v141
	s_waitcnt lgkmcnt(0)
	v_add_f32_e32 v141, v70, v142
	v_add_f32_e32 v142, v71, v143
	v_add_f32_e32 v143, v72, v144
	v_max3_f32 v66, v66, v139, v140
	v_add_f32_e32 v144, v73, v145
	v_max3_f32 v66, v66, v141, v142
	v_max3_f32 v145, v66, v143, v144
	ds_read_b128 v[66:69], v134 offset:36928
	ds_read_b128 v[70:73], v134 offset:36944
	s_waitcnt lgkmcnt(1)
	v_add_f32_e32 v74, v74, v66
	v_add_f32_e32 v75, v75, v67
	v_add_f32_e32 v76, v76, v68
	v_add_f32_e32 v77, v77, v69
	s_waitcnt lgkmcnt(0)
	v_add_f32_e32 v78, v78, v70
	v_add_f32_e32 v67, v79, v71
	v_max3_f32 v66, v145, v74, v75
	v_mov_b32_e32 v145, v67
	v_add_f32_e32 v148, v80, v72
	v_max3_f32 v66, v66, v76, v77
	v_add_f32_e32 v81, v81, v73
	v_max3_f32 v66, v66, v78, v145
	v_max3_f32 v79, v66, v148, v81
	ds_read_b128 v[66:69], v134 offset:36992
	ds_read_b128 v[70:73], v134 offset:37008
	s_waitcnt lgkmcnt(1)
	v_add_f32_e32 v66, v50, v66
	v_add_f32_e32 v67, v51, v67
	v_add_f32_e32 v68, v52, v68
	v_add_f32_e32 v69, v53, v69
	s_waitcnt lgkmcnt(0)
	v_add_f32_e32 v70, v54, v70
	v_add_f32_e32 v71, v55, v71
	v_add_f32_e32 v72, v56, v72
	v_max3_f32 v50, v79, v66, v67
	v_max3_f32 v50, v50, v68, v69
	v_add_f32_e32 v73, v57, v73
	v_max3_f32 v50, v50, v70, v71
	v_max3_f32 v79, v50, v72, v73
	ds_read_b128 v[50:53], v134 offset:37056
	ds_read_b128 v[54:57], v134 offset:37072
	s_waitcnt lgkmcnt(1)
	v_add_f32_e32 v149, v58, v50
	v_add_f32_e32 v59, v59, v51
	v_add_f32_e32 v51, v60, v52
	v_max3_f32 v50, v79, v149, v59
	v_mov_b32_e32 v79, v51
	v_add_f32_e32 v61, v61, v53
	s_waitcnt lgkmcnt(0)
	v_add_f32_e32 v62, v62, v54
	v_add_f32_e32 v55, v63, v55
	v_add_f32_e32 v162, v64, v56
	v_add_u32_e32 v0, 55, v0
	v_max3_f32 v50, v50, v79, v61
	v_add_f32_e32 v163, v65, v57
	v_max3_f32 v50, v50, v62, v55
	v_and_b32_e32 v51, 64, v207
	v_max3_f32 v0, v50, v162, v163
	v_xor_b32_e32 v50, 32, v207
	v_add_u32_e32 v51, 64, v51
	v_cmp_lt_i32_e32 vcc, v50, v51
	s_nop 1
	v_cndmask_b32_e32 v50, v207, v50, vcc
	v_lshlrev_b32_e32 v50, 2, v50
	ds_bpermute_b32 v50, v50, v0
	s_waitcnt lgkmcnt(0)
	v_max3_f32 v63, v136, v0, v50
	v_sub_f32_e32 v52, v139, v63
	v_exp_f32_e32 v167, v52
	v_sub_f32_e32 v52, v68, v63
	v_sub_f32_e32 v56, v141, v63
	v_sub_f32_e32 v0, v137, v63
	v_exp_f32_e32 v168, v52
	v_sub_f32_e32 v52, v140, v63
	v_exp_f32_e32 v140, v56
	v_sub_f32_e32 v56, v70, v63
	v_sub_f32_e32 v60, v143, v63
	v_exp_f32_e32 v165, v0
	v_sub_f32_e32 v0, v66, v63
	v_exp_f32_e32 v141, v56
	v_sub_f32_e32 v56, v142, v63
	v_exp_f32_e32 v142, v60
	v_sub_f32_e32 v60, v72, v63
	v_sub_f32_e32 v66, v74, v63
	v_exp_f32_e32 v143, v60
	v_sub_f32_e32 v60, v144, v63
	v_exp_f32_e32 v144, v66
	v_sub_f32_e32 v66, v149, v63
	v_exp_f32_e32 v149, v66
	v_sub_f32_e32 v66, v75, v63
	v_sub_f32_e32 v59, v59, v63
	v_exp_f32_e32 v68, v66
	v_exp_f32_e32 v66, v59
	v_sub_f32_e32 v59, v76, v63
	v_exp_f32_e32 v169, v59
	v_sub_f32_e32 v59, v79, v63
	v_exp_f32_e32 v166, v0
	v_sub_f32_e32 v0, v138, v63
	v_sub_f32_e32 v50, v67, v63
	v_exp_f32_e32 v170, v59
	v_sub_f32_e32 v59, v77, v63
	v_exp_f32_e32 v0, v0
	v_exp_f32_e32 v50, v50
	v_exp_f32_e32 v76, v59
	v_sub_f32_e32 v59, v61, v63
	v_exp_f32_e32 v74, v59
	v_sub_f32_e32 v59, v78, v63
	v_sub_f32_e32 v55, v55, v63
	v_exp_f32_e32 v54, v52
	v_sub_f32_e32 v52, v69, v63
	v_exp_f32_e32 v171, v59
	v_sub_f32_e32 v59, v62, v63
	v_exp_f32_e32 v78, v55
	v_sub_f32_e32 v55, v148, v63
	v_add_f32_e32 v51, v166, v165
	v_exp_f32_e32 v52, v52
	v_exp_f32_e32 v172, v59
	v_sub_f32_e32 v59, v145, v63
	v_exp_f32_e32 v145, v55
	v_sub_f32_e32 v55, v162, v63
	v_exp_f32_e32 v58, v56
	v_sub_f32_e32 v56, v71, v63
	v_exp_f32_e32 v148, v55
	v_sub_f32_e32 v55, v81, v63
	v_add_f32_e32 v70, v50, v0
	v_add_f32_e32 v71, v51, v1
	v_exp_f32_e32 v138, v55
	v_sub_f32_e32 v55, v163, v63
	v_add_f32_e32 v71, v70, v71
	v_sub_f32_e32 v164, v136, v63
	v_add_f32_e32 v53, v168, v167
	v_exp_f32_e32 v56, v56
	v_exp_f32_e32 v136, v55
	v_mov_b32_e32 v55, v71
	v_add_f32_e32 v70, v52, v54
	v_add_f32_e32 v71, v53, v55
	v_sub_f32_e32 v64, v73, v63
	v_add_f32_e32 v71, v70, v71
	v_add_f32_e32 v57, v141, v140
	v_exp_f32_e32 v60, v60
	v_exp_f32_e32 v64, v64
	v_exp_f32_e32 v80, v59
	v_mov_b32_e32 v59, v71
	v_add_f32_e32 v70, v56, v58
	v_add_f32_e32 v71, v57, v59
	v_add_f32_e32 v65, v143, v142
	v_add_f32_e32 v71, v70, v71
	v_mov_b32_e32 v61, v71
	v_add_f32_e32 v70, v64, v60
	v_add_f32_e32 v71, v65, v61
	v_add_f32_e32 v67, v149, v144
	v_add_f32_e32 v71, v70, v71
	v_mov_b32_e32 v69, v71
	v_add_f32_e32 v70, v66, v68
	v_add_f32_e32 v71, v67, v69
	v_add_f32_e32 v75, v170, v169
	v_add_f32_e32 v71, v70, v71
	v_mov_b32_e32 v77, v71
	v_add_f32_e32 v70, v74, v76
	v_add_f32_e32 v71, v75, v77
	v_add_f32_e32 v79, v172, v171
	v_add_f32_e32 v71, v70, v71
	v_mov_b32_e32 v81, v71
	v_add_f32_e32 v70, v78, v80
	v_add_f32_e32 v71, v79, v81
	v_add_f32_e32 v137, v148, v145
	v_add_f32_e32 v71, v70, v71
	v_mov_b32_e32 v139, v71
	v_exp_f32_e32 v62, v164
	v_add_f32_e32 v70, v136, v138
	v_add_f32_e32 v71, v137, v139
	v_cvt_pk_bf16_f32 v72, v140, v58
	v_add_f32_e32 v65, v70, v71
	v_cvt_pk_bf16_f32 v70, v165, v0
	v_add_u32_e32 v0, v132, v122
	v_cvt_pk_bf16_f32 v71, v167, v54
	v_cvt_pk_bf16_f32 v73, v142, v60
	v_cvt_pk_bf16_f32 v58, v144, v68
	v_cvt_pk_bf16_f32 v59, v169, v76
	v_cvt_pk_bf16_f32 v60, v171, v80
	v_cvt_pk_bf16_f32 v54, v166, v50
	v_cvt_pk_bf16_f32 v55, v168, v52
	v_cvt_pk_bf16_f32 v50, v149, v66
	v_cvt_pk_bf16_f32 v51, v170, v74
	v_cvt_pk_bf16_f32 v52, v172, v78
	ds_read_b128 v[66:69], v0 offset:23040
	ds_read_b128 v[74:77], v0 offset:18432
	ds_read_b128 v[78:81], v0 offset:18464
	v_mul_f32_e32 v16, v62, v16
	v_mul_f32_e32 v17, v62, v17
	v_mul_f32_e32 v14, v62, v14
	v_mul_f32_e32 v15, v62, v15
	v_mul_f32_e32 v12, v62, v12
	v_mul_f32_e32 v13, v62, v13
	v_mul_f32_e32 v10, v62, v10
	v_mul_f32_e32 v11, v62, v11
	v_mul_f32_e32 v8, v62, v8
	v_mul_f32_e32 v9, v62, v9
	v_mul_f32_e32 v6, v62, v6
	v_mul_f32_e32 v7, v62, v7
	v_mul_f32_e32 v4, v62, v4
	v_mul_f32_e32 v5, v62, v5
	v_mul_f32_e32 v2, v62, v2
	v_mul_f32_e32 v3, v62, v3
	v_mul_f32_e32 v32, v62, v32
	v_mul_f32_e32 v33, v62, v33
	v_mul_f32_e32 v30, v62, v30
	v_mul_f32_e32 v31, v62, v31
	v_mul_f32_e32 v28, v62, v28
	v_mul_f32_e32 v29, v62, v29
	v_mul_f32_e32 v26, v62, v26
	v_mul_f32_e32 v27, v62, v27
	v_mul_f32_e32 v24, v62, v24
	v_mul_f32_e32 v25, v62, v25
	v_mul_f32_e32 v22, v62, v22
	v_mul_f32_e32 v23, v62, v23
	v_mul_f32_e32 v20, v62, v20
	v_mul_f32_e32 v21, v62, v21
	v_mul_f32_e32 v18, v62, v18
	v_mul_f32_e32 v19, v62, v19
	s_waitcnt lgkmcnt(2)
	v_mfma_f32_32x32x16_bf16 v[2:17], v[66:69], v[70:73], v[2:17]
	ds_read_b128 v[66:69], v0 offset:23072
	v_cvt_pk_bf16_f32 v61, v145, v138
	v_cvt_pk_bf16_f32 v56, v141, v56
	v_cvt_pk_bf16_f32 v57, v143, v64
	v_cvt_pk_bf16_f32 v53, v148, v136
	v_fmac_f32_e32 v65, v133, v62
	v_mov_b32_e32 v133, v65
	s_waitcnt lgkmcnt(2)
	v_mfma_f32_32x32x16_bf16 v[18:33], v[74:77], v[70:73], v[18:33]
	v_mov_b32_e32 v136, v63
	s_waitcnt lgkmcnt(1)
	v_mfma_f32_32x32x16_bf16 v[18:33], v[78:81], v[58:61], v[18:33]
	s_waitcnt lgkmcnt(0)
	v_mfma_f32_32x32x16_bf16 v[2:17], v[66:69], v[58:61], v[2:17]
	ds_read_b128 v[58:61], v0 offset:18496
	ds_read_b128 v[66:69], v0 offset:23104
	s_waitcnt lgkmcnt(1)
	v_mfma_f32_32x32x16_bf16 v[18:33], v[58:61], v[54:57], v[18:33]
	s_waitcnt lgkmcnt(0)
	v_mfma_f32_32x32x16_bf16 v[2:17], v[66:69], v[54:57], v[2:17]
	ds_read_b128 v[54:57], v0 offset:18528
	ds_read_b128 v[58:61], v0 offset:23136
	s_waitcnt lgkmcnt(1)
	v_mfma_f32_32x32x16_bf16 v[18:33], v[54:57], v[50:53], v[18:33]
	s_waitcnt lgkmcnt(0)
	v_mfma_f32_32x32x16_bf16 v[2:17], v[58:61], v[50:53], v[2:17]
	s_branch .Lattn_join_A
